# P4 fused tiles: every v_pk_add_f32 in the row-sum chains split into two v_add_f32 (bit-identical)
# speedup vs baseline: 1.0090x; 1.0090x over previous
.LBB0_658:
	s_and_b64 vcc, exec, s[0:1]
	s_cbranch_vccz .LBB0_653
	s_lshl_b32 s0, s76, 14
	s_or_b32 s76, s0, s21
	s_lshl_b32 s77, s77, 6
	s_add_i32 s78, s77, 63
	s_cmp_gt_i32 s78, s72
	s_cbranch_scc1 .Lflt_no
	s_cmp_lt_i32 s77, s71
	s_cbranch_scc1 .Lflt_no
	s_sub_i32 s0, s33, s78
	s_cmpk_gt_i32 s0, 0x7f
	s_cselect_b64 s[0:1], -1, 0
	s_or_b64 s[0:1], s[0:1], s[30:31]
	s_and_b64 vcc, exec, s[0:1]
	s_cbranch_vccz .Lflt_no
	v_add_u32_e32 v3, s76, v198
	ds_read_b128 v[4:7], v3
	v_add_u32_e32 v16, s76, v206
	ds_read_b128 v[8:11], v16
	v_add_u32_e32 v17, s76, v207
	ds_read_b128 v[12:15], v17
	v_add_u32_e32 v238, s76, v208
	ds_read_b128 v[214:217], v238
	ds_read_b128 v[234:237], v3 offset:4096
	ds_read_b128 v[244:247], v16 offset:4096
	ds_read_b128 v[248:251], v17 offset:4096
	ds_read_b128 v[252:255], v238 offset:4096
	s_setprio 1
	s_waitcnt lgkmcnt(7)
	v_mfma_f32_32x32x16_bf16 v[118:133], v[4:7], v[134:137], v[86:101]
	s_waitcnt lgkmcnt(6)
	v_mfma_f32_32x32x16_bf16 v[118:133], v[8:11], v[138:141], v[118:133]
	s_waitcnt lgkmcnt(5)
	v_mfma_f32_32x32x16_bf16 v[118:133], v[12:15], v[142:145], v[118:133]
	s_waitcnt lgkmcnt(4)
	v_mfma_f32_32x32x16_bf16 v[118:133], v[214:217], v[150:153], v[118:133]
	s_add_i32 s0, s76, 0x2000
	v_mfma_f32_32x32x16_bf16 v[102:117], v[4:7], v[146:149], v[86:101]
	v_add_u32_e32 v3, s0, v200
	ds_read_b64_tr_b16 v[4:5], v3 offset:0
	ds_read_b64_tr_b16 v[6:7], v3 offset:1024
	v_mfma_f32_32x32x16_bf16 v[102:117], v[8:11], v[154:157], v[102:117]
	ds_read_b64_tr_b16 v[8:9], v3 offset:2048
	ds_read_b64_tr_b16 v[10:11], v3 offset:3072
	s_nop 4
	v_exp_f32_e32 v118, v118
	v_exp_f32_e32 v119, v119
	v_exp_f32_e32 v120, v120
	v_mfma_f32_32x32x16_bf16 v[102:117], v[12:15], v[158:161], v[102:117]
	v_add_u32_e32 v3, s0, v201
	ds_read_b64_tr_b16 v[12:13], v3 offset:0
	ds_read_b64_tr_b16 v[14:15], v3 offset:1024
	v_exp_f32_e32 v121, v121
	v_exp_f32_e32 v122, v122
	v_exp_f32_e32 v123, v123
	v_mfma_f32_32x32x16_bf16 v[102:117], v[214:217], v[162:165], v[102:117]
	ds_read_b64_tr_b16 v[214:215], v3 offset:2048
	ds_read_b64_tr_b16 v[216:217], v3 offset:3072
	v_exp_f32_e32 v124, v124
	v_exp_f32_e32 v125, v125
	v_exp_f32_e32 v126, v126
	s_waitcnt lgkmcnt(8)
	v_mfma_f32_32x32x16_bf16 v[218:233], v[234:237], v[134:137], v[86:101]
	v_exp_f32_e32 v127, v127
	v_exp_f32_e32 v128, v128
	v_exp_f32_e32 v129, v129
	v_mfma_f32_32x32x16_bf16 v[218:233], v[244:247], v[138:141], v[218:233]
	v_exp_f32_e32 v130, v130
	v_exp_f32_e32 v131, v131
	v_exp_f32_e32 v132, v132
	v_mfma_f32_32x32x16_bf16 v[218:233], v[248:251], v[142:145], v[218:233]
	v_exp_f32_e32 v133, v133
	v_add_f32_e32 v16, v118, v120
	v_add_f32_e32 v17, v119, v121
	v_add_f32_e32 v16, v16, v122
	v_add_f32_e32 v17, v17, v123
	v_add_f32_e32 v16, v16, v124
	v_add_f32_e32 v17, v17, v125
	v_cvt_pk_bf16_f32 v118, v118, v119
	v_cvt_pk_bf16_f32 v119, v120, v121
	v_cvt_pk_bf16_f32 v120, v122, v123
	v_mfma_f32_32x32x16_bf16 v[218:233], v[252:255], v[150:153], v[218:233]
	v_cvt_pk_bf16_f32 v121, v124, v125
	v_cvt_pk_bf16_f32 v122, v126, v127
	v_cvt_pk_bf16_f32 v123, v128, v129
	v_cvt_pk_bf16_f32 v124, v130, v131
	v_cvt_pk_bf16_f32 v125, v132, v133
	v_add_f32_e32 v16, v16, v126
	v_add_f32_e32 v17, v17, v127
	v_add_f32_e32 v16, v16, v128
	v_add_f32_e32 v17, v17, v129
	v_add_f32_e32 v16, v16, v130
	v_add_f32_e32 v17, v17, v131
	v_add_f32_e32 v16, v16, v132
	v_add_f32_e32 v17, v17, v133
	s_waitcnt lgkmcnt(0)
	v_mfma_f32_32x32x16_bf16 v[20:35], v[4:7], v[118:121], v[20:35]
	v_exp_f32_e32 v102, v102
	v_exp_f32_e32 v103, v103
	v_exp_f32_e32 v104, v104
	v_mfma_f32_32x32x16_bf16 v[36:51], v[12:15], v[118:121], v[36:51]
	v_exp_f32_e32 v105, v105
	v_exp_f32_e32 v106, v106
	v_exp_f32_e32 v107, v107
	v_mfma_f32_32x32x16_bf16 v[20:35], v[8:11], v[122:125], v[20:35]
	v_exp_f32_e32 v108, v108
	v_exp_f32_e32 v109, v109
	v_exp_f32_e32 v110, v110
	v_mfma_f32_32x32x16_bf16 v[36:51], v[214:217], v[122:125], v[36:51]
	v_exp_f32_e32 v111, v111
	v_exp_f32_e32 v112, v112
	v_exp_f32_e32 v113, v113
	s_add_i32 s0, s76, 0x3000
	v_mfma_f32_32x32x16_bf16 v[118:133], v[234:237], v[146:149], v[86:101]
	v_add_u32_e32 v3, s0, v200
	ds_read_b64_tr_b16 v[234:235], v3 offset:0
	ds_read_b64_tr_b16 v[236:237], v3 offset:1024
	v_exp_f32_e32 v114, v114
	v_exp_f32_e32 v115, v115
	v_exp_f32_e32 v116, v116
	v_mfma_f32_32x32x16_bf16 v[118:133], v[244:247], v[154:157], v[118:133]
	ds_read_b64_tr_b16 v[244:245], v3 offset:2048
	ds_read_b64_tr_b16 v[246:247], v3 offset:3072
	v_exp_f32_e32 v117, v117
	v_add_f32_e32 v238, v102, v104
	v_add_f32_e32 v239, v103, v105
	v_add_f32_e32 v238, v238, v106
	v_add_f32_e32 v239, v239, v107
	v_add_f32_e32 v238, v238, v108
	v_add_f32_e32 v239, v239, v109
	v_cvt_pk_bf16_f32 v102, v102, v103
	v_cvt_pk_bf16_f32 v103, v104, v105
	v_mfma_f32_32x32x16_bf16 v[118:133], v[248:251], v[158:161], v[118:133]
	v_add_u32_e32 v3, s0, v201
	ds_read_b64_tr_b16 v[248:249], v3 offset:0
	ds_read_b64_tr_b16 v[250:251], v3 offset:1024
	v_cvt_pk_bf16_f32 v104, v106, v107
	v_cvt_pk_bf16_f32 v105, v108, v109
	v_cvt_pk_bf16_f32 v106, v110, v111
	v_cvt_pk_bf16_f32 v107, v112, v113
	v_cvt_pk_bf16_f32 v108, v114, v115
	v_cvt_pk_bf16_f32 v109, v116, v117
	v_mfma_f32_32x32x16_bf16 v[118:133], v[252:255], v[162:165], v[118:133]
	ds_read_b64_tr_b16 v[252:253], v3 offset:2048
	ds_read_b64_tr_b16 v[254:255], v3 offset:3072
	v_add_f32_e32 v238, v238, v110
	v_add_f32_e32 v239, v239, v111
	v_add_f32_e32 v238, v238, v112
	v_add_f32_e32 v239, v239, v113
	v_add_f32_e32 v238, v238, v114
	v_add_f32_e32 v239, v239, v115
	v_add_f32_e32 v238, v238, v116
	v_add_f32_e32 v239, v239, v117
	v_mfma_f32_32x32x16_bf16 v[68:83], v[4:7], v[102:105], v[68:83]
	v_exp_f32_e32 v218, v218
	v_exp_f32_e32 v219, v219
	v_exp_f32_e32 v220, v220
	v_mfma_f32_32x32x16_bf16 v[52:67], v[12:15], v[102:105], v[52:67]
	v_exp_f32_e32 v221, v221
	v_exp_f32_e32 v222, v222
	v_exp_f32_e32 v223, v223
	v_mfma_f32_32x32x16_bf16 v[68:83], v[8:11], v[106:109], v[68:83]
	v_exp_f32_e32 v224, v224
	v_exp_f32_e32 v225, v225
	v_exp_f32_e32 v226, v226
	v_mfma_f32_32x32x16_bf16 v[52:67], v[214:217], v[106:109], v[52:67]
	v_exp_f32_e32 v227, v227
	v_exp_f32_e32 v228, v228
	v_exp_f32_e32 v229, v229
	v_exp_f32_e32 v230, v230
	v_exp_f32_e32 v231, v231
	v_exp_f32_e32 v232, v232
	v_exp_f32_e32 v233, v233
	v_add_f32_e32 v16, v16, v218
	v_add_f32_e32 v17, v17, v219
	v_add_f32_e32 v16, v16, v220
	v_add_f32_e32 v17, v17, v221
	v_add_f32_e32 v16, v16, v222
	v_add_f32_e32 v17, v17, v223
	v_add_f32_e32 v16, v16, v224
	v_add_f32_e32 v17, v17, v225
	v_cvt_pk_bf16_f32 v218, v218, v219
	v_cvt_pk_bf16_f32 v219, v220, v221
	v_cvt_pk_bf16_f32 v220, v222, v223
	v_cvt_pk_bf16_f32 v221, v224, v225
	v_cvt_pk_bf16_f32 v222, v226, v227
	v_cvt_pk_bf16_f32 v223, v228, v229
	v_cvt_pk_bf16_f32 v224, v230, v231
	v_cvt_pk_bf16_f32 v225, v232, v233
	s_waitcnt lgkmcnt(0)
	v_mfma_f32_32x32x16_bf16 v[20:35], v[234:237], v[218:221], v[20:35]
	v_exp_f32_e32 v118, v118
	v_exp_f32_e32 v119, v119
	v_exp_f32_e32 v120, v120
	v_mfma_f32_32x32x16_bf16 v[36:51], v[248:251], v[218:221], v[36:51]
	v_exp_f32_e32 v121, v121
	v_exp_f32_e32 v122, v122
	v_exp_f32_e32 v123, v123
	v_mfma_f32_32x32x16_bf16 v[20:35], v[244:247], v[222:225], v[20:35]
	v_exp_f32_e32 v124, v124
	v_exp_f32_e32 v125, v125
	v_exp_f32_e32 v126, v126
	v_mfma_f32_32x32x16_bf16 v[36:51], v[252:255], v[222:225], v[36:51]
	v_exp_f32_e32 v127, v127
	v_exp_f32_e32 v128, v128
	v_exp_f32_e32 v129, v129
	v_exp_f32_e32 v130, v130
	v_exp_f32_e32 v131, v131
	v_exp_f32_e32 v132, v132
	v_exp_f32_e32 v133, v133
	v_add_f32_e32 v238, v238, v118
	v_add_f32_e32 v239, v239, v119
	v_add_f32_e32 v238, v238, v120
	v_add_f32_e32 v239, v239, v121
	v_add_f32_e32 v238, v238, v122
	v_add_f32_e32 v239, v239, v123
	v_add_f32_e32 v238, v238, v124
	v_add_f32_e32 v239, v239, v125
	v_cvt_pk_bf16_f32 v118, v118, v119
	v_cvt_pk_bf16_f32 v119, v120, v121
	v_cvt_pk_bf16_f32 v120, v122, v123
	v_cvt_pk_bf16_f32 v121, v124, v125
	v_cvt_pk_bf16_f32 v122, v126, v127
	v_cvt_pk_bf16_f32 v123, v128, v129
	v_cvt_pk_bf16_f32 v124, v130, v131
	v_cvt_pk_bf16_f32 v125, v132, v133
	v_mfma_f32_32x32x16_bf16 v[68:83], v[234:237], v[118:121], v[68:83]
	v_add_f32_e32 v16, v16, v226
	v_add_f32_e32 v17, v17, v227
	v_add_f32_e32 v16, v16, v228
	v_add_f32_e32 v17, v17, v229
	v_mfma_f32_32x32x16_bf16 v[52:67], v[248:251], v[118:121], v[52:67]
	v_add_f32_e32 v16, v16, v230
	v_add_f32_e32 v17, v17, v231
	v_add_f32_e32 v16, v16, v232
	v_add_f32_e32 v17, v17, v233
	v_mfma_f32_32x32x16_bf16 v[68:83], v[244:247], v[122:125], v[68:83]
	v_add_f32_e32 v238, v238, v126
	v_add_f32_e32 v239, v239, v127
	v_add_f32_e32 v238, v238, v128
	v_add_f32_e32 v239, v239, v129
	v_mfma_f32_32x32x16_bf16 v[52:67], v[252:255], v[122:125], v[52:67]
	v_add_f32_e32 v238, v238, v130
	v_add_f32_e32 v239, v239, v131
	v_add_f32_e32 v238, v238, v132
	v_add_f32_e32 v239, v239, v133
	s_setprio 0
	v_add_f32_e32 v16, v16, v17
	v_add_f32_e32 v238, v238, v239
	v_add_f32_e32 v180, v180, v16
	v_add_f32_e32 v181, v181, v238
	s_branch .LBB0_653

.Lfg0_nomask:
	s_nop 1
	v_exp_f32_e32 v118, v118
	v_exp_f32_e32 v119, v119
	v_exp_f32_e32 v120, v120
	v_exp_f32_e32 v121, v121
	v_exp_f32_e32 v122, v122
	v_exp_f32_e32 v123, v123
	v_exp_f32_e32 v124, v124
	v_exp_f32_e32 v125, v125
	v_exp_f32_e32 v126, v126
	v_exp_f32_e32 v127, v127
	v_exp_f32_e32 v128, v128
	v_exp_f32_e32 v129, v129
	v_exp_f32_e32 v130, v130
	v_exp_f32_e32 v131, v131
	v_exp_f32_e32 v132, v132
	v_exp_f32_e32 v133, v133
	v_add_f32_e32 v16, v118, v120
	v_add_f32_e32 v17, v119, v121
	v_add_f32_e32 v16, v16, v122
	v_add_f32_e32 v17, v17, v123
	v_add_f32_e32 v16, v16, v124
	v_add_f32_e32 v17, v17, v125
	v_cvt_pk_bf16_f32 v118, v118, v119
	v_cvt_pk_bf16_f32 v119, v120, v121
	v_cvt_pk_bf16_f32 v120, v122, v123
	v_cvt_pk_bf16_f32 v121, v124, v125
	v_cvt_pk_bf16_f32 v122, v126, v127
	v_cvt_pk_bf16_f32 v123, v128, v129
	v_cvt_pk_bf16_f32 v124, v130, v131
	v_cvt_pk_bf16_f32 v125, v132, v133
	v_add_f32_e32 v16, v16, v126
	v_add_f32_e32 v17, v17, v127
	v_add_f32_e32 v16, v16, v128
	v_add_f32_e32 v17, v17, v129
	v_add_f32_e32 v16, v16, v130
	v_add_f32_e32 v17, v17, v131
	v_add_f32_e32 v16, v16, v132
	v_add_f32_e32 v17, v17, v133
	s_waitcnt lgkmcnt(0)
	v_mfma_f32_32x32x16_bf16 v[20:35], v[234:237], v[118:121], v[20:35]
	v_exp_f32_e32 v102, v102
	v_exp_f32_e32 v103, v103
	v_exp_f32_e32 v104, v104
	v_mfma_f32_32x32x16_bf16 v[36:51], v[248:251], v[118:121], v[36:51]
	v_exp_f32_e32 v105, v105
	v_exp_f32_e32 v106, v106
	v_exp_f32_e32 v107, v107
	v_mfma_f32_32x32x16_bf16 v[20:35], v[244:247], v[122:125], v[20:35]
	v_exp_f32_e32 v108, v108
	v_exp_f32_e32 v109, v109
	v_exp_f32_e32 v110, v110
	v_mfma_f32_32x32x16_bf16 v[36:51], v[252:255], v[122:125], v[36:51]
	v_exp_f32_e32 v111, v111
	v_exp_f32_e32 v112, v112
	v_exp_f32_e32 v113, v113
	v_exp_f32_e32 v114, v114
	v_exp_f32_e32 v115, v115
	v_exp_f32_e32 v116, v116
	v_exp_f32_e32 v117, v117
	v_add_f32_e32 v238, v102, v104
	v_add_f32_e32 v239, v103, v105
	v_add_f32_e32 v238, v238, v106
	v_add_f32_e32 v239, v239, v107
	v_add_f32_e32 v238, v238, v108
	v_add_f32_e32 v239, v239, v109
	v_cvt_pk_bf16_f32 v102, v102, v103
	v_cvt_pk_bf16_f32 v103, v104, v105
	v_cvt_pk_bf16_f32 v104, v106, v107
	v_cvt_pk_bf16_f32 v105, v108, v109
	v_cvt_pk_bf16_f32 v106, v110, v111
	v_cvt_pk_bf16_f32 v107, v112, v113
	v_cvt_pk_bf16_f32 v108, v114, v115
	v_cvt_pk_bf16_f32 v109, v116, v117
	v_mfma_f32_32x32x16_bf16 v[68:83], v[234:237], v[102:105], v[68:83]
	v_add_f32_e32 v238, v238, v110
	v_add_f32_e32 v239, v239, v111
	v_add_f32_e32 v238, v238, v112
	v_add_f32_e32 v239, v239, v113
	v_mfma_f32_32x32x16_bf16 v[52:67], v[248:251], v[102:105], v[52:67]
	v_add_f32_e32 v238, v238, v114
	v_add_f32_e32 v239, v239, v115
	v_add_f32_e32 v238, v238, v116
	v_add_f32_e32 v239, v239, v117
	v_mfma_f32_32x32x16_bf16 v[68:83], v[244:247], v[106:109], v[68:83]
	v_add_f32_e32 v16, v16, v17
	v_mfma_f32_32x32x16_bf16 v[52:67], v[252:255], v[106:109], v[52:67]
	v_add_f32_e32 v180, v180, v16
	s_setprio 0
	v_add_f32_e32 v238, v238, v239
	v_add_f32_e32 v181, v181, v238

.Lfg1_nomask:
	s_nop 1
	v_exp_f32_e32 v118, v118
	v_exp_f32_e32 v119, v119
	v_exp_f32_e32 v120, v120
	v_exp_f32_e32 v121, v121
	v_exp_f32_e32 v122, v122
	v_exp_f32_e32 v123, v123
	v_exp_f32_e32 v124, v124
	v_exp_f32_e32 v125, v125
	v_exp_f32_e32 v126, v126
	v_exp_f32_e32 v127, v127
	v_exp_f32_e32 v128, v128
	v_exp_f32_e32 v129, v129
	v_exp_f32_e32 v130, v130
	v_exp_f32_e32 v131, v131
	v_exp_f32_e32 v132, v132
	v_exp_f32_e32 v133, v133
	v_add_f32_e32 v16, v118, v120
	v_add_f32_e32 v17, v119, v121
	v_add_f32_e32 v16, v16, v122
	v_add_f32_e32 v17, v17, v123
	v_add_f32_e32 v16, v16, v124
	v_add_f32_e32 v17, v17, v125
	v_cvt_pk_bf16_f32 v118, v118, v119
	v_cvt_pk_bf16_f32 v119, v120, v121
	v_cvt_pk_bf16_f32 v120, v122, v123
	v_cvt_pk_bf16_f32 v121, v124, v125
	v_cvt_pk_bf16_f32 v122, v126, v127
	v_cvt_pk_bf16_f32 v123, v128, v129
	v_cvt_pk_bf16_f32 v124, v130, v131
	v_cvt_pk_bf16_f32 v125, v132, v133
	v_add_f32_e32 v16, v16, v126
	v_add_f32_e32 v17, v17, v127
	v_add_f32_e32 v16, v16, v128
	v_add_f32_e32 v17, v17, v129
	v_add_f32_e32 v16, v16, v130
	v_add_f32_e32 v17, v17, v131
	v_add_f32_e32 v16, v16, v132
	v_add_f32_e32 v17, v17, v133
	s_waitcnt lgkmcnt(0)
	v_mfma_f32_32x32x16_bf16 v[20:35], v[234:237], v[118:121], v[20:35]
	v_exp_f32_e32 v102, v102
	v_exp_f32_e32 v103, v103
	v_exp_f32_e32 v104, v104
	v_mfma_f32_32x32x16_bf16 v[36:51], v[248:251], v[118:121], v[36:51]
	v_exp_f32_e32 v105, v105
	v_exp_f32_e32 v106, v106
	v_exp_f32_e32 v107, v107
	v_mfma_f32_32x32x16_bf16 v[20:35], v[244:247], v[122:125], v[20:35]
	v_exp_f32_e32 v108, v108
	v_exp_f32_e32 v109, v109
	v_exp_f32_e32 v110, v110
	v_mfma_f32_32x32x16_bf16 v[36:51], v[252:255], v[122:125], v[36:51]
	v_exp_f32_e32 v111, v111
	v_exp_f32_e32 v112, v112
	v_exp_f32_e32 v113, v113
	v_exp_f32_e32 v114, v114
	v_exp_f32_e32 v115, v115
	v_exp_f32_e32 v116, v116
	v_exp_f32_e32 v117, v117
	v_add_f32_e32 v238, v102, v104
	v_add_f32_e32 v239, v103, v105
	v_add_f32_e32 v238, v238, v106
	v_add_f32_e32 v239, v239, v107
	v_add_f32_e32 v238, v238, v108
	v_add_f32_e32 v239, v239, v109
	v_cvt_pk_bf16_f32 v102, v102, v103
	v_cvt_pk_bf16_f32 v103, v104, v105
	v_cvt_pk_bf16_f32 v104, v106, v107
	v_cvt_pk_bf16_f32 v105, v108, v109
	v_cvt_pk_bf16_f32 v106, v110, v111
	v_cvt_pk_bf16_f32 v107, v112, v113
	v_cvt_pk_bf16_f32 v108, v114, v115
	v_cvt_pk_bf16_f32 v109, v116, v117
	v_mfma_f32_32x32x16_bf16 v[68:83], v[234:237], v[102:105], v[68:83]
	v_add_f32_e32 v238, v238, v110
	v_add_f32_e32 v239, v239, v111
	v_add_f32_e32 v238, v238, v112
	v_add_f32_e32 v239, v239, v113
	v_mfma_f32_32x32x16_bf16 v[52:67], v[248:251], v[102:105], v[52:67]
	v_add_f32_e32 v238, v238, v114
	v_add_f32_e32 v239, v239, v115
	v_add_f32_e32 v238, v238, v116
	v_add_f32_e32 v239, v239, v117
	v_mfma_f32_32x32x16_bf16 v[68:83], v[244:247], v[106:109], v[68:83]
	v_add_f32_e32 v16, v16, v17
	v_mfma_f32_32x32x16_bf16 v[52:67], v[252:255], v[106:109], v[52:67]
	v_add_f32_e32 v180, v180, v16
	s_setprio 0
	v_add_f32_e32 v238, v238, v239
	v_add_f32_e32 v181, v181, v238
	s_branch .LBB0_653
